# stacked: sel fast path on raw scores with per-MFMA-gap exp interleave, permlane32_swap row-max exchange in all attention loops
# speedup vs baseline: 1.0043x; 1.0043x over previous
; #define LAS __attribute__((address_space(3)))
; __device__ __forceinline__ int crow(int r, int hi) { return (r & 3) + 8 * (r >> 2) + 4 * hi; }
; template <int NKS, int KRS>
; __device__ __forceinline__ void qk_tile(f32x16& p0, f32x16& p1, const LAS unsigned char* Kt, const bf16x8 (&qf)[NKS], int r32, int hi) {
;     ...
;         if (ks + 2 < NKS) { a0[(ks + 2) % 3] = *(const LAS bf16x8*)(kb + (ks + 2) * 32); a1[(ks + 2) % 3] = *(const LAS bf16x8*)(kb + 32 * KRS + (ks + 2) * 32); }
;         p0 = __builtin_amdgcn_mfma_f32_32x32x16_bf16(a0[ks % 3], qf[ks], p0, 0, 0, 0);
;         p1 = __builtin_amdgcn_mfma_f32_32x32x16_bf16(a1[ks % 3], qf[ks], p1, 0, 0, 0);
;         __builtin_amdgcn_sched_barrier(0);
;     }
; __device__ __forceinline__ void nsa_unit(int hk, int T, LAS unsigned char* lds, LAS float* wsf, const AttnPtrs& P) {
;     ...
;         qk_tile<8, KRS_NSA>(p0, p1, buf, qf, r32, hi);
; #pragma unroll
;         for (int r = 0; r < 16; ++r) { const int c = 64 * t + crow(r, hi); if (c > mycmax) p0[r] = -INFINITY; if (c + 32 > mycmax) p1[r] = -INFINITY; }
.LBB0_1406:
	s_mul_i32 s14, s14, 0x8c00
	v_add_u32_e32 v64, s14, v60
	ds_read_b128 v[2:5], v64
	ds_read_b128 v[68:71], v64 offset:32
	ds_read_b128 v[18:21], v64 offset:8704
	ds_read_b128 v[72:75], v64 offset:8736
	ds_read_b128 v[76:79], v64 offset:64
	ds_read_b128 v[80:83], v64 offset:8768
	s_waitcnt lgkmcnt(5)
	v_mfma_f32_32x32x16_bf16 v[2:17], v[2:5], v[112:115], 0
	s_waitcnt lgkmcnt(3)
	v_mfma_f32_32x32x16_bf16 v[18:33], v[18:21], v[112:115], 0
	v_mfma_f32_32x32x16_bf16 v[2:17], v[68:71], v[116:119], v[2:17]
	ds_read_b128 v[68:71], v64 offset:96
	ds_read_b128 v[84:87], v64 offset:8800
	s_waitcnt lgkmcnt(4)
	v_mfma_f32_32x32x16_bf16 v[18:33], v[72:75], v[116:119], v[18:33]
	s_waitcnt lgkmcnt(3)
	v_mfma_f32_32x32x16_bf16 v[2:17], v[76:79], v[120:123], v[2:17]
	ds_read_b128 v[72:75], v64 offset:128
	ds_read_b128 v[76:79], v64 offset:8832
	s_waitcnt lgkmcnt(4)
	v_mfma_f32_32x32x16_bf16 v[18:33], v[80:83], v[120:123], v[18:33]
	s_waitcnt lgkmcnt(3)
	v_mfma_f32_32x32x16_bf16 v[2:17], v[68:71], v[124:127], v[2:17]
	ds_read_b128 v[68:71], v64 offset:160
	ds_read_b128 v[80:83], v64 offset:8864
	s_waitcnt lgkmcnt(4)
	v_mfma_f32_32x32x16_bf16 v[18:33], v[84:87], v[124:127], v[18:33]
	s_waitcnt lgkmcnt(3)
	v_mfma_f32_32x32x16_bf16 v[2:17], v[72:75], v[128:131], v[2:17]
	ds_read_b128 v[72:75], v64 offset:192
	ds_read_b128 v[84:87], v64 offset:8896
	s_waitcnt lgkmcnt(4)
	v_mfma_f32_32x32x16_bf16 v[18:33], v[76:79], v[128:131], v[18:33]
	s_waitcnt lgkmcnt(3)
	v_mfma_f32_32x32x16_bf16 v[2:17], v[68:71], v[132:135], v[2:17]
	ds_read_b128 v[68:71], v64 offset:224
	ds_read_b128 v[76:79], v64 offset:8928
	s_waitcnt lgkmcnt(4)
	v_mfma_f32_32x32x16_bf16 v[18:33], v[80:83], v[132:135], v[18:33]
	s_waitcnt lgkmcnt(3)
	v_mfma_f32_32x32x16_bf16 v[2:17], v[72:75], v[136:139], v[2:17]
	s_waitcnt lgkmcnt(2)
	v_mfma_f32_32x32x16_bf16 v[18:33], v[84:87], v[136:139], v[18:33]
	s_waitcnt lgkmcnt(1)
	v_mfma_f32_32x32x16_bf16 v[2:17], v[68:71], v[140:143], v[2:17]
	s_waitcnt lgkmcnt(0)
	v_mfma_f32_32x32x16_bf16 v[18:33], v[76:79], v[140:143], v[18:33]
	v_add_u32_e32 v64, s60, v61
	v_add_u32_e32 v67, 0xffffffa0, v64
	v_add_u32_e32 v65, 0xffffff80, v64
	v_cmp_le_i32_e32 vcc, v67, v0
	v_lshl_add_u64 v[52:53], v[52:53], 0, s[68:69]
	s_nop 6
	v_cndmask_b32_e32 v18, v185, v18, vcc
	v_cmp_lt_i32_e32 vcc, v65, v0
	s_barrier
; __device__ __forceinline__ int crow(int r, int hi) { return (r & 3) + 8 * (r >> 2) + 4 * hi; }
; template <bool WITH_O>
; __device__ __forceinline__ void softmax_step(float& m, float& l, f32x16 (&o)[4], f32x16& p0, f32x16& p1, LAS float* wsf, int r32, int hi) {
;     float mxa = fmaxf(fmaxf(p0[0], p1[0]), p0[1]), mxb = fmaxf(fmaxf(p1[1], p0[2]), p1[2]);
; #pragma unroll
;     for (int r = 3; r < 15; r += 2) { mxa = fmaxf(fmaxf(mxa, p0[r]), p1[r]); mxb = fmaxf(fmaxf(mxb, p0[r + 1]), p1[r + 1]); }
;     float mx = fmaxf(fmaxf(mxa, mxb), fmaxf(p0[15], p1[15]));
;     mx = fmaxf(mx, __shfl_xor(mx, 32));
;     const bool grow = __any(mx > m + 8.f);
;     const float mnew = grow ? fmaxf(m, mx) : m;
;     const float f = grow ? __builtin_amdgcn_exp2f(m - mnew) : 1.f;
;     m = mnew;
;     float s = 0.f;
; #pragma unroll
;     for (int r = 0; r < 16; ++r) { p0[r] = __builtin_amdgcn_exp2f(p0[r] - mnew); p1[r] = __builtin_amdgcn_exp2f(p1[r] - mnew); s += p0[r] + p1[r]; }
;     l = l * f + s;
; __device__ __forceinline__ void nsa_unit(int hk, int T, LAS unsigned char* lds, LAS float* wsf, const AttnPtrs& P) {
;     ...
;         for (int r = 0; r < 16; ++r) { const int c = 64 * t + crow(r, hi); if (c > mycmax) p0[r] = -INFINITY; if (c + 32 > mycmax) p1[r] = -INFINITY; }
;         softmax_step<false>(m, l, o, p0, p1, wsf, r32, hi);
	s_nop 0
	v_cndmask_b32_e32 v3, v185, v3, vcc
	v_cmp_le_i32_e32 vcc, v65, v0
	v_add_u32_e32 v65, 0xffffffa1, v64
	s_nop 0
	v_cndmask_b32_e32 v2, v185, v2, vcc
	v_cmp_le_i32_e32 vcc, v65, v0
	v_add_u32_e32 v65, 0xffffff82, v64
	s_nop 0
	v_cndmask_b32_e32 v19, v185, v19, vcc
	v_cmp_le_i32_e32 vcc, v65, v0
	v_add_u32_e32 v65, 0xffffffa2, v64
	s_nop 0
	v_cndmask_b32_e32 v4, v185, v4, vcc
	v_cmp_le_i32_e32 vcc, v65, v0
	v_add_u32_e32 v65, 0xffffff83, v64
	s_nop 0
	v_cndmask_b32_e32 v20, v185, v20, vcc
	v_cmp_le_i32_e32 vcc, v65, v0
	v_add_u32_e32 v65, 0xffffffa3, v64
	s_nop 0
	v_cndmask_b32_e32 v5, v185, v5, vcc
	v_cmp_le_i32_e32 vcc, v65, v0
	v_add_u32_e32 v65, 0xffffff88, v64
	s_nop 0
	v_cndmask_b32_e32 v21, v185, v21, vcc
	v_cmp_le_i32_e32 vcc, v65, v0
	v_add_u32_e32 v65, 0xffffffa8, v64
	s_nop 0
	v_cndmask_b32_e32 v6, v185, v6, vcc
	v_cmp_le_i32_e32 vcc, v65, v0
	v_add_u32_e32 v65, 0xffffff89, v64
	s_nop 0
	v_cndmask_b32_e32 v22, v185, v22, vcc
	v_cmp_le_i32_e32 vcc, v65, v0
	v_add_u32_e32 v65, 0xffffffa9, v64
	s_nop 0
	v_cndmask_b32_e32 v7, v185, v7, vcc
	v_cmp_le_i32_e32 vcc, v65, v0
	v_add_u32_e32 v65, 0xffffff8a, v64
	s_nop 0
	v_cndmask_b32_e32 v23, v185, v23, vcc
	v_cmp_le_i32_e32 vcc, v65, v0
	v_add_u32_e32 v65, 0xffffffaa, v64
	s_nop 0
	v_cndmask_b32_e32 v8, v185, v8, vcc
	v_cmp_le_i32_e32 vcc, v65, v0
	v_add_u32_e32 v65, 0xffffff8b, v64
	s_nop 0
	v_cndmask_b32_e32 v24, v185, v24, vcc
	v_cmp_le_i32_e32 vcc, v65, v0
	v_add_u32_e32 v65, 0xffffffab, v64
	s_nop 0
	v_cndmask_b32_e32 v9, v185, v9, vcc
	v_cmp_le_i32_e32 vcc, v65, v0
	v_add_u32_e32 v65, 0xffffff90, v64
	s_nop 0
	v_cndmask_b32_e32 v25, v185, v25, vcc
	v_cmp_le_i32_e32 vcc, v65, v0
	v_add_u32_e32 v65, 0xffffffb0, v64
	s_nop 0
	v_cndmask_b32_e32 v10, v185, v10, vcc
	v_cmp_le_i32_e32 vcc, v65, v0
	v_add_u32_e32 v65, 0xffffff91, v64
	s_nop 0
	v_cndmask_b32_e32 v26, v185, v26, vcc
	v_cmp_le_i32_e32 vcc, v65, v0
	v_add_u32_e32 v65, 0xffffffb1, v64
	s_nop 0
	v_cndmask_b32_e32 v11, v185, v11, vcc
	v_cmp_le_i32_e32 vcc, v65, v0
	v_add_u32_e32 v65, 0xffffff92, v64
	s_nop 0
	v_cndmask_b32_e32 v27, v185, v27, vcc
	v_cmp_le_i32_e32 vcc, v65, v0
	v_add_u32_e32 v65, 0xffffffb2, v64
	s_nop 0
	v_cndmask_b32_e32 v12, v185, v12, vcc
	v_cmp_le_i32_e32 vcc, v65, v0
	v_add_u32_e32 v65, 0xffffff93, v64
	s_nop 0
	v_cndmask_b32_e32 v28, v185, v28, vcc
	v_cmp_le_i32_e32 vcc, v65, v0
	v_add_u32_e32 v65, 0xffffffb3, v64
	s_nop 0
	v_cndmask_b32_e32 v13, v185, v13, vcc
	v_cmp_le_i32_e32 vcc, v65, v0
	v_add_u32_e32 v65, 0xffffff98, v64
	s_nop 0
	v_cndmask_b32_e32 v29, v185, v29, vcc
	v_cmp_le_i32_e32 vcc, v65, v0
	v_add_u32_e32 v65, 0xffffffb8, v64
	s_nop 0
	v_cndmask_b32_e32 v14, v185, v14, vcc
	v_cmp_le_i32_e32 vcc, v65, v0
	v_add_u32_e32 v65, 0xffffff99, v64
	s_nop 0
	v_cndmask_b32_e32 v30, v185, v30, vcc
	v_cmp_le_i32_e32 vcc, v65, v0
	v_add_u32_e32 v65, 0xffffffb9, v64
	s_nop 0
	v_cndmask_b32_e32 v15, v185, v15, vcc
	v_cmp_le_i32_e32 vcc, v65, v0
	v_add_u32_e32 v65, 0xffffff9a, v64
	s_nop 0
	v_cndmask_b32_e32 v31, v185, v31, vcc
	v_cmp_le_i32_e32 vcc, v65, v0
	v_add_u32_e32 v65, 0xffffffba, v64
	s_nop 0
	v_cndmask_b32_e32 v16, v185, v16, vcc
	v_cmp_le_i32_e32 vcc, v65, v0
	v_add_u32_e32 v65, 0xffffff9b, v64
	v_add_u32_e32 v64, 0xffffffbb, v64
	v_cndmask_b32_e32 v32, v185, v32, vcc
	v_cmp_le_i32_e32 vcc, v65, v0
	v_max3_f32 v65, v19, v4, v20
	v_max3_f32 v65, v65, v6, v22
	v_cndmask_b32_e32 v17, v185, v17, vcc
	v_cmp_le_i32_e32 vcc, v64, v0
	v_max3_f32 v64, v2, v18, v3
	v_max3_f32 v64, v64, v5, v21
	v_max3_f32 v64, v64, v7, v23
	v_max3_f32 v65, v65, v8, v24
	v_max3_f32 v64, v64, v9, v25
	v_max3_f32 v65, v65, v10, v26
	v_cndmask_b32_e32 v33, v185, v33, vcc
	v_max3_f32 v64, v64, v11, v27
	v_max3_f32 v65, v65, v12, v28
	v_max3_f32 v64, v64, v13, v29
	v_max3_f32 v65, v65, v14, v30
	v_max_f32_e32 v67, v33, v33
	v_max_f32_e32 v68, v17, v17
	v_max3_f32 v64, v64, v15, v31
	v_max3_f32 v65, v65, v16, v32
	v_max_f32_e32 v67, v68, v67
	v_max3_f32 v64, v64, v65, v67
	v_mov_b32_e32 v65, v64
	s_nop 1
	v_permlane32_swap_b32_e32 v65, v64
	v_max_f32_e32 v64, v64, v65
	v_add_f32_e32 v65, 0x41000000, v63
	v_cmp_gt_f32_e32 vcc, v64, v65
	s_cmp_eq_u64 vcc, 0
	v_max_f32_e32 v65, v63, v63
	v_max_f32_e32 v64, v65, v64
	s_cselect_b64 vcc, -1, 0
	v_cndmask_b32_e32 v156, v64, v63, vcc
	v_sub_f32_e32 v2, v2, v156
	v_sub_f32_e32 v18, v18, v156
	v_exp_f32_e32 v2, v2
	v_exp_f32_e32 v18, v18
	v_sub_f32_e32 v3, v3, v156
	v_exp_f32_e32 v3, v3
	v_sub_f32_e32 v4, v4, v156
	v_add_f32_e32 v2, v2, v18
	v_sub_f32_e32 v18, v19, v156
	v_exp_f32_e32 v18, v18
	v_sub_f32_e32 v19, v20, v156
	v_add_f32_e32 v2, 0, v2
	v_exp_f32_e32 v4, v4
	v_add_f32_e32 v3, v3, v18
	v_exp_f32_e32 v19, v19
	v_add_f32_e32 v18, v3, v2
	v_sub_f32_e32 v2, v5, v156
	v_exp_f32_e32 v20, v2
	v_sub_f32_e32 v2, v21, v156
	v_exp_f32_e32 v21, v2
	v_sub_f32_e32 v2, v6, v156
	v_exp_f32_e32 v3, v2
	v_sub_f32_e32 v2, v22, v156
	v_add_f32_e32 v19, v4, v19
	v_exp_f32_e32 v5, v2
	v_sub_f32_e32 v2, v7, v156
	v_sub_f32_e32 v4, v23, v156
	v_exp_f32_e32 v2, v2
	v_exp_f32_e32 v4, v4
	v_add_f32_e32 v6, v19, v18
	v_add_f32_e32 v7, v20, v21
	v_add_f32_e32 v6, v7, v6
	v_pk_add_f32 v[2:3], v[2:3], v[4:5]
	v_sub_f32_e32 v4, v25, v156
	v_add_f32_e32 v3, v3, v6
	v_add_f32_e32 v18, v2, v3
	v_sub_f32_e32 v2, v8, v156
	v_exp_f32_e32 v3, v2
	v_sub_f32_e32 v2, v24, v156
	v_exp_f32_e32 v5, v2
	v_sub_f32_e32 v2, v9, v156
	v_sub_f32_e32 v6, v10, v156
	v_exp_f32_e32 v2, v2
	v_exp_f32_e32 v4, v4
	v_exp_f32_e32 v7, v6
	v_sub_f32_e32 v6, v26, v156
	v_exp_f32_e32 v9, v6
	v_sub_f32_e32 v6, v11, v156
	v_sub_f32_e32 v8, v27, v156
	v_exp_f32_e32 v6, v6
	v_exp_f32_e32 v8, v8
	v_pk_add_f32 v[2:3], v[2:3], v[4:5]
	s_add_i32 s60, s60, 64
	v_add_f32_e32 v3, v3, v18
	v_add_f32_e32 v4, v2, v3
	v_pk_add_f32 v[2:3], v[6:7], v[8:9]
	v_sub_f32_e32 v6, v14, v156
	v_add_f32_e32 v3, v3, v4
	v_add_f32_e32 v10, v2, v3
	v_sub_f32_e32 v2, v12, v156
	v_exp_f32_e32 v3, v2
	v_sub_f32_e32 v2, v28, v156
	v_exp_f32_e32 v5, v2
	v_sub_f32_e32 v2, v13, v156
	v_sub_f32_e32 v4, v29, v156
	v_exp_f32_e32 v2, v2
	v_exp_f32_e32 v4, v4
	v_exp_f32_e32 v7, v6
	v_sub_f32_e32 v6, v30, v156
	v_exp_f32_e32 v9, v6
	v_sub_f32_e32 v6, v15, v156
	v_sub_f32_e32 v8, v31, v156
	v_exp_f32_e32 v6, v6
	v_exp_f32_e32 v8, v8
	v_pk_add_f32 v[2:3], v[2:3], v[4:5]
	s_cmp_lg_u32 s16, s12
	v_add_f32_e32 v3, v3, v10
	v_add_f32_e32 v4, v2, v3
	v_pk_add_f32 v[2:3], v[6:7], v[8:9]
	v_sub_f32_e32 v6, v33, v156
	v_add_f32_e32 v3, v3, v4
	v_sub_f32_e32 v4, v16, v156
	v_exp_f32_e32 v5, v4
	v_sub_f32_e32 v4, v32, v156
	v_exp_f32_e32 v7, v4
	v_sub_f32_e32 v4, v17, v156
	v_exp_f32_e32 v4, v4
	v_exp_f32_e32 v6, v6
	v_add_f32_e32 v8, v2, v3
	v_sub_f32_e32 v2, v63, v156
	v_exp_f32_e32 v9, v2
	v_pk_add_f32 v[2:3], v[4:5], v[6:7]
	s_nop 0
	v_add_f32_e32 v3, v3, v8
	v_add_f32_e32 v67, v2, v3
	v_cndmask_b32_e64 v2, v9, 1.0, vcc
	v_fmac_f32_e32 v67, v62, v2
	s_cbranch_scc0 .LBB0_1408
	v_mov_b32_e32 v62, v67
	v_mov_b32_e32 v63, v156
	s_mov_b32 s13, s12
	s_and_b32 s14, s13, 1
	s_add_i32 s12, s13, 1
	s_cmp_ge_u32 s12, s16
	s_cbranch_scc0 .LBB0_1403
	s_branch .LBB0_1404

; __device__ __forceinline__ int crow(int r, int hi) { return (r & 3) + 8 * (r >> 2) + 4 * hi; }
; template <bool WITH_O>
; __device__ __forceinline__ void softmax_step(float& m, float& l, f32x16 (&o)[4], f32x16& p0, f32x16& p1, LAS float* wsf, int r32, int hi) {
;     float mxa = fmaxf(fmaxf(p0[0], p1[0]), p0[1]), mxb = fmaxf(fmaxf(p1[1], p0[2]), p1[2]);
; #pragma unroll
;     for (int r = 3; r < 15; r += 2) { mxa = fmaxf(fmaxf(mxa, p0[r]), p1[r]); mxb = fmaxf(fmaxf(mxb, p0[r + 1]), p1[r + 1]); }
;     float mx = fmaxf(fmaxf(mxa, mxb), fmaxf(p0[15], p1[15]));
;     mx = fmaxf(mx, __shfl_xor(mx, 32));
;     const bool grow = __any(mx > m + 8.f);
;     const float mnew = grow ? fmaxf(m, mx) : m;
;     const float f = grow ? __builtin_amdgcn_exp2f(m - mnew) : 1.f;
;     m = mnew;
;     float s = 0.f;
; #pragma unroll
;     for (int r = 0; r < 16; ++r) { p0[r] = __builtin_amdgcn_exp2f(p0[r] - mnew); p1[r] = __builtin_amdgcn_exp2f(p1[r] - mnew); s += p0[r] + p1[r]; }
;     l = l * f + s;
; __device__ __forceinline__ void nsa_unit(int hk, int T, LAS unsigned char* lds, LAS float* wsf, const AttnPtrs& P) {
;     ...
;             const unsigned uw = __builtin_amdgcn_readfirstlane(uni[w * 8 + (j >> 5)]);
;             const bool act = ((uw >> (j & 31)) & 1u) != 0u;
;             f32x16 p0, p1;
;             if (act) {
;                 qk_tile<8, KRS_NSA>(p0, p1, buf, qf, r32, hi);
;                 const unsigned mw = sel[(8 * w + qi) * 8 + (j >> 5)];
;                 const bool mine = (mw >> (j & 31)) & 1u;
; #pragma unroll
;                 for (int r = 0; r < 16; ++r) { const int key = 64 * j + crow(r, hi);
;                     if (!mine || key > tq) p0[r] = -INFINITY; if (!mine || key + 32 > tq) p1[r] = -INFINITY; }
;                 softmax_step<true>(m, l, o, p0, p1, wsf, r32, hi);
.LBB0_1458:
	s_lshr_b32 s6, s11, 5
	s_lshl_b32 s8, 1, s11
	v_readlane_b32 s9, v253, s6
	s_and_b32 s9, s9, s8
	s_cmp_eq_u32 s9, 0
	s_cbranch_scc1 .LBB0_1464
	s_mul_i32 s7, s7, 0x8c00
	s_add_i32 s12, s7, 0
	v_add3_u32 v0, s12, v195, v166
	v_lshl_add_u32 v254, s6, 2, v196
	ds_read_b32 v254, v254
	ds_read_b128 v[2:5], v0
	ds_read_b128 v[6:9], v0 offset:32
	ds_read_b128 v[10:13], v0 offset:8704
	ds_read_b128 v[202:205], v0 offset:8736
	s_waitcnt lgkmcnt(3)
	v_mfma_f32_32x32x16_bf16 v[96:111], v[2:5], v[112:115], 0
	ds_read_b128 v[2:5], v0 offset:64
	ds_read_b128 v[206:209], v0 offset:8768
	s_waitcnt lgkmcnt(3)
	v_mfma_f32_32x32x16_bf16 v[64:79], v[10:13], v[112:115], 0
	v_mfma_f32_32x32x16_bf16 v[96:111], v[6:9], v[116:119], v[96:111]
	ds_read_b128 v[6:9], v0 offset:96
	ds_read_b128 v[10:13], v0 offset:8800
	s_waitcnt lgkmcnt(4)
	v_mfma_f32_32x32x16_bf16 v[64:79], v[202:205], v[116:119], v[64:79]
	s_waitcnt lgkmcnt(3)
	v_mfma_f32_32x32x16_bf16 v[96:111], v[2:5], v[120:123], v[96:111]
	ds_read_b128 v[2:5], v0 offset:128
	ds_read_b128 v[202:205], v0 offset:8832
	s_waitcnt lgkmcnt(4)
	v_mfma_f32_32x32x16_bf16 v[64:79], v[206:209], v[120:123], v[64:79]
	s_waitcnt lgkmcnt(3)
	v_mfma_f32_32x32x16_bf16 v[96:111], v[6:9], v[124:127], v[96:111]
	ds_read_b128 v[6:9], v0 offset:160
	ds_read_b128 v[206:209], v0 offset:8864
	s_waitcnt lgkmcnt(4)
	v_mfma_f32_32x32x16_bf16 v[64:79], v[10:13], v[124:127], v[64:79]
	s_waitcnt lgkmcnt(3)
	v_mfma_f32_32x32x16_bf16 v[96:111], v[2:5], v[128:131], v[96:111]
	ds_read_b128 v[2:5], v0 offset:192
	ds_read_b128 v[10:13], v0 offset:8896
	s_waitcnt lgkmcnt(4)
	v_mfma_f32_32x32x16_bf16 v[64:79], v[202:205], v[128:131], v[64:79]
	s_waitcnt lgkmcnt(3)
	v_mfma_f32_32x32x16_bf16 v[96:111], v[6:9], v[132:135], v[96:111]
	ds_read_b128 v[6:9], v0 offset:224
	ds_read_b128 v[202:205], v0 offset:8928
	s_waitcnt lgkmcnt(4)
	v_mfma_f32_32x32x16_bf16 v[64:79], v[206:209], v[132:135], v[64:79]
	s_waitcnt lgkmcnt(3)
	v_mfma_f32_32x32x16_bf16 v[96:111], v[2:5], v[136:139], v[96:111]
	s_waitcnt lgkmcnt(2)
	v_mfma_f32_32x32x16_bf16 v[64:79], v[10:13], v[136:139], v[64:79]
	s_waitcnt lgkmcnt(1)
	v_mfma_f32_32x32x16_bf16 v[96:111], v[6:9], v[140:143], v[96:111]
	s_waitcnt lgkmcnt(0)
	v_mfma_f32_32x32x16_bf16 v[64:79], v[202:205], v[140:143], v[64:79]
	v_and_b32_e32 v0, s8, v254
	v_cmp_eq_u32_e32 vcc, 0, v0
	s_cmp_eq_u32 s11, s97
	s_cbranch_scc1 .Lsel_lastmask
	s_mov_b64 s[98:99], vcc
	s_nop 6
	v_max3_f32 v2, v96, v64, v97
	v_max3_f32 v3, v65, v98, v66
	v_max3_f32 v2, v2, v99, v67
	v_max3_f32 v3, v3, v100, v68
	v_max3_f32 v2, v2, v101, v69
	v_max3_f32 v3, v3, v102, v70
	v_max3_f32 v2, v2, v103, v71
	v_max3_f32 v3, v3, v104, v72
	v_max3_f32 v2, v2, v105, v73
	v_max3_f32 v3, v3, v106, v74
	v_max3_f32 v2, v2, v107, v75
	v_max3_f32 v3, v3, v108, v76
	v_max3_f32 v2, v2, v109, v77
	v_max3_f32 v3, v3, v110, v78
	v_max3_f32 v2, v2, v111, v79
	v_max_f32_e32 v2, v2, v3
	v_cndmask_b32_e64 v2, v2, v185, s[98:99]
	v_mov_b32_e32 v3, v2
	s_nop 1
	v_permlane32_swap_b32_e32 v3, v2
	v_max_f32_e32 v2, v2, v3
	v_add_f32_e32 v3, 0x41000000, v200
	v_cmp_gt_f32_e32 vcc, v2, v3
	s_cmp_eq_u64 vcc, 0
	v_max_f32_e32 v3, v200, v200
	v_max_f32_e32 v0, v3, v2
	s_cselect_b64 s[6:7], -1, 0
	v_cndmask_b32_e64 v0, v0, v200, s[6:7]
	v_sub_f32_e32 v14, v200, v0
	v_exp_f32_e32 v14, v14
	v_mov_b32_e32 v15, 0x7f800000
	v_cndmask_b32_e64 v15, v0, v15, s[98:99]
	s_and_b64 vcc, exec, s[6:7]
	s_cbranch_vccnz .Lsel_f_nogrow
	s_and_saveexec_b64 s[8:9], s[4:5]
	ds_write_b32 v192, v14
	s_or_b64 exec, exec, s[8:9]
	s_waitcnt lgkmcnt(0)
	ds_read_b128 v[2:5], v193 offset:96
	ds_read_b128 v[6:9], v193 offset:64
	ds_read_b128 v[10:13], v193 offset:32
	ds_read_b128 v[202:205], v193
	s_waitcnt lgkmcnt(3)
	v_pk_mul_f32 v[60:61], v[60:61], v[2:3]
	s_waitcnt lgkmcnt(2)
	v_pk_mul_f32 v[56:57], v[56:57], v[6:7]
	s_waitcnt lgkmcnt(1)
	v_pk_mul_f32 v[52:53], v[52:53], v[10:11]
	v_pk_mul_f32 v[62:63], v[62:63], v[4:5]
	v_pk_mul_f32 v[58:59], v[58:59], v[8:9]
	v_pk_mul_f32 v[54:55], v[54:55], v[12:13]
	s_waitcnt lgkmcnt(0)
	v_pk_mul_f32 v[50:51], v[50:51], v[204:205]
	v_pk_mul_f32 v[48:49], v[48:49], v[202:203]
	v_pk_mul_f32 v[44:45], v[44:45], v[2:3]
	v_pk_mul_f32 v[40:41], v[40:41], v[6:7]
	v_pk_mul_f32 v[36:37], v[36:37], v[10:11]
	v_pk_mul_f32 v[46:47], v[46:47], v[4:5]
	v_pk_mul_f32 v[42:43], v[42:43], v[8:9]
	v_pk_mul_f32 v[38:39], v[38:39], v[12:13]
	v_pk_mul_f32 v[34:35], v[34:35], v[204:205]
	v_pk_mul_f32 v[32:33], v[32:33], v[202:203]
	v_pk_mul_f32 v[28:29], v[28:29], v[2:3]
	v_pk_mul_f32 v[24:25], v[24:25], v[6:7]
	v_pk_mul_f32 v[20:21], v[20:21], v[10:11]
	v_pk_mul_f32 v[30:31], v[30:31], v[4:5]
	v_pk_mul_f32 v[26:27], v[26:27], v[8:9]
	v_pk_mul_f32 v[22:23], v[22:23], v[12:13]
	v_pk_mul_f32 v[18:19], v[18:19], v[204:205]
	v_pk_mul_f32 v[16:17], v[16:17], v[202:203]
	v_pk_mul_f32 v[92:93], v[92:93], v[2:3]
	v_pk_mul_f32 v[88:89], v[88:89], v[6:7]
	v_pk_mul_f32 v[84:85], v[84:85], v[10:11]
	v_pk_mul_f32 v[94:95], v[94:95], v[4:5]
	v_pk_mul_f32 v[90:91], v[90:91], v[8:9]
	v_pk_mul_f32 v[86:87], v[86:87], v[12:13]
	v_pk_mul_f32 v[82:83], v[82:83], v[204:205]
	v_pk_mul_f32 v[80:81], v[80:81], v[202:203]
; #define LAS __attribute__((address_space(3)))
; __device__ __forceinline__ unsigned pk2(float lo, float hi) { f32x2 v = {lo, hi}; bf16x2_t b = __builtin_convertvector(v, bf16x2_t); return __builtin_bit_cast(unsigned, b); }
; #define PV_LD(i_) do { vf[(i_) & 3] = *(const LAS bf16x8*)(vb2 + ((i_) & 3) * 32 * VRS + ((i_) >> 2) * 32); } while (0)
; __device__ __forceinline__ void pv_tile(f32x16 (&o)[4], const f32x16& p0, const f32x16& p1, const LAS unsigned char* Vt, int r32, int hi) {
;     bf16x8 pa[4];
; #pragma unroll
;     for (int s = 0; s < 4; ++s) { const int b = 8 * (s & 1); u32x4 w;
;         if (s < 2) { w.x = pk2(p0[b], p0[b + 1]); w.y = pk2(p0[b + 2], p0[b + 3]); w.z = pk2(p0[b + 4], p0[b + 5]); w.w = pk2(p0[b + 6], p0[b + 7]); }
;         else { w.x = pk2(p1[b], p1[b + 1]); w.y = pk2(p1[b + 2], p1[b + 3]); w.z = pk2(p1[b + 4], p1[b + 5]); w.w = pk2(p1[b + 6], p1[b + 7]); }
;         pa[s] = __builtin_bit_cast(bf16x8, w); }
;     const LAS unsigned char* vb2 = Vt + r32 * VRS + hi * 16;
;     bf16x8 vf[4];
;     ...
;     PV_LD(0); PV_LD(1); PV_LD(2);
;     __builtin_amdgcn_sched_barrier(0);
; #pragma unroll
;     for (int i = 0; i < 16; ++i) {
;         if (i + 3 < 16) PV_LD(i + 3);
;         o[i & 3] = __builtin_amdgcn_mfma_f32_32x32x16_bf16(pa[i >> 2], vf[i & 3], o[i & 3], 0, 0, 0);
;         __builtin_amdgcn_sched_barrier(0);
;     }
; template <bool WITH_O>
; __device__ __forceinline__ void softmax_step(float& m, float& l, f32x16 (&o)[4], f32x16& p0, f32x16& p1, LAS float* wsf, int r32, int hi) {
;     ...
;     for (int r = 0; r < 16; ++r) { p0[r] = __builtin_amdgcn_exp2f(p0[r] - mnew); p1[r] = __builtin_amdgcn_exp2f(p1[r] - mnew); s += p0[r] + p1[r]; }
;     l = l * f + s;
.Lsel_f_nogrow:
	v_add3_u32 v201, s12, v198, v166
	ds_read_b128 v[2:5], v201 offset:17408
	ds_read_b128 v[6:9], v201 offset:22016
	ds_read_b128 v[10:13], v201 offset:26624
	v_sub_f32_e32 v96, v96, v15
	v_sub_f32_e32 v97, v97, v15
	v_sub_f32_e32 v98, v98, v15
	v_sub_f32_e32 v99, v99, v15
	v_sub_f32_e32 v100, v100, v15
	v_sub_f32_e32 v101, v101, v15
	v_sub_f32_e32 v102, v102, v15
	v_sub_f32_e32 v103, v103, v15
	v_exp_f32_e32 v96, v96
	v_exp_f32_e32 v97, v97
	v_exp_f32_e32 v98, v98
	v_exp_f32_e32 v99, v99
	v_exp_f32_e32 v100, v100
	v_exp_f32_e32 v101, v101
	v_exp_f32_e32 v102, v102
	v_exp_f32_e32 v103, v103
	v_add_f32_e32 v200, v96, v97
	v_add_f32_e32 v200, v200, v98
	v_add_f32_e32 v200, v200, v99
	v_add_f32_e32 v200, v200, v100
	v_add_f32_e32 v200, v200, v101
	v_cvt_pk_bf16_f32 v202, v96, v97
	v_cvt_pk_bf16_f32 v203, v98, v99
	v_cvt_pk_bf16_f32 v204, v100, v101
	v_cvt_pk_bf16_f32 v205, v102, v103
	v_add_f32_e32 v200, v200, v102
	v_add_f32_e32 v200, v200, v103
	s_nop 1
	s_waitcnt lgkmcnt(2)
	v_mfma_f32_32x32x16_bf16 v[48:63], v[202:205], v[2:5], v[48:63]
	ds_read_b128 v[2:5], v201 offset:31232
	v_sub_f32_e32 v104, v104, v15
	v_sub_f32_e32 v105, v105, v15
	v_sub_f32_e32 v106, v106, v15
	v_sub_f32_e32 v107, v107, v15
	v_sub_f32_e32 v108, v108, v15
	v_sub_f32_e32 v109, v109, v15
	v_sub_f32_e32 v110, v110, v15
	s_waitcnt lgkmcnt(2)
	v_mfma_f32_32x32x16_bf16 v[32:47], v[202:205], v[6:9], v[32:47]
	ds_read_b128 v[6:9], v201 offset:17440
	v_sub_f32_e32 v111, v111, v15
	v_exp_f32_e32 v104, v104
	v_exp_f32_e32 v105, v105
	v_exp_f32_e32 v106, v106
	v_exp_f32_e32 v107, v107
	v_exp_f32_e32 v108, v108
	v_exp_f32_e32 v109, v109
	s_waitcnt lgkmcnt(2)
	v_mfma_f32_32x32x16_bf16 v[16:31], v[202:205], v[10:13], v[16:31]
	ds_read_b128 v[10:13], v201 offset:22048
	v_exp_f32_e32 v110, v110
	v_exp_f32_e32 v111, v111
	v_add_f32_e32 v200, v200, v104
	v_add_f32_e32 v200, v200, v105
	v_add_f32_e32 v200, v200, v106
	v_add_f32_e32 v200, v200, v107
	v_add_f32_e32 v200, v200, v108
	s_waitcnt lgkmcnt(2)
	v_mfma_f32_32x32x16_bf16 v[80:95], v[202:205], v[2:5], v[80:95]
	ds_read_b128 v[2:5], v201 offset:26656
	v_cvt_pk_bf16_f32 v206, v104, v105
	v_cvt_pk_bf16_f32 v207, v106, v107
	v_cvt_pk_bf16_f32 v208, v108, v109
	v_cvt_pk_bf16_f32 v209, v110, v111
	v_add_f32_e32 v200, v200, v109
	v_add_f32_e32 v200, v200, v110
	v_add_f32_e32 v200, v200, v111
	s_waitcnt lgkmcnt(2)
	v_mfma_f32_32x32x16_bf16 v[48:63], v[206:209], v[6:9], v[48:63]
	ds_read_b128 v[6:9], v201 offset:31264
	v_sub_f32_e32 v64, v64, v15
	v_sub_f32_e32 v65, v65, v15
	v_sub_f32_e32 v66, v66, v15
	v_sub_f32_e32 v67, v67, v15
	v_sub_f32_e32 v68, v68, v15
	v_sub_f32_e32 v69, v69, v15
	v_sub_f32_e32 v70, v70, v15
	s_waitcnt lgkmcnt(2)
	v_mfma_f32_32x32x16_bf16 v[32:47], v[206:209], v[10:13], v[32:47]
	ds_read_b128 v[10:13], v201 offset:17472
	v_sub_f32_e32 v71, v71, v15
	v_exp_f32_e32 v64, v64
	v_exp_f32_e32 v65, v65
	v_exp_f32_e32 v66, v66
	v_exp_f32_e32 v67, v67
	v_exp_f32_e32 v68, v68
	v_exp_f32_e32 v69, v69
	s_waitcnt lgkmcnt(2)
	v_mfma_f32_32x32x16_bf16 v[16:31], v[206:209], v[2:5], v[16:31]
	ds_read_b128 v[2:5], v201 offset:22080
	v_exp_f32_e32 v70, v70
	v_exp_f32_e32 v71, v71
	v_add_f32_e32 v200, v200, v64
	v_add_f32_e32 v200, v200, v65
	v_add_f32_e32 v200, v200, v66
	v_add_f32_e32 v200, v200, v67
	v_add_f32_e32 v200, v200, v68
	s_waitcnt lgkmcnt(2)
	v_mfma_f32_32x32x16_bf16 v[80:95], v[206:209], v[6:9], v[80:95]
	ds_read_b128 v[6:9], v201 offset:26688
	v_cvt_pk_bf16_f32 v202, v64, v65
	v_cvt_pk_bf16_f32 v203, v66, v67
	v_cvt_pk_bf16_f32 v204, v68, v69
	v_cvt_pk_bf16_f32 v205, v70, v71
	v_add_f32_e32 v200, v200, v69
	v_add_f32_e32 v200, v200, v70
	v_add_f32_e32 v200, v200, v71
	s_waitcnt lgkmcnt(2)
	v_mfma_f32_32x32x16_bf16 v[48:63], v[202:205], v[10:13], v[48:63]
	ds_read_b128 v[10:13], v201 offset:31296
	v_sub_f32_e32 v72, v72, v15
	v_sub_f32_e32 v73, v73, v15
	v_sub_f32_e32 v74, v74, v15
	v_sub_f32_e32 v75, v75, v15
	v_sub_f32_e32 v76, v76, v15
	v_sub_f32_e32 v77, v77, v15
	v_sub_f32_e32 v78, v78, v15
	s_waitcnt lgkmcnt(2)
	v_mfma_f32_32x32x16_bf16 v[32:47], v[202:205], v[2:5], v[32:47]
	ds_read_b128 v[2:5], v201 offset:17504
	v_sub_f32_e32 v79, v79, v15
	v_exp_f32_e32 v72, v72
	v_exp_f32_e32 v73, v73
	v_exp_f32_e32 v74, v74
	v_exp_f32_e32 v75, v75
	v_exp_f32_e32 v76, v76
	v_exp_f32_e32 v77, v77
	s_waitcnt lgkmcnt(2)
	v_mfma_f32_32x32x16_bf16 v[16:31], v[202:205], v[6:9], v[16:31]
	ds_read_b128 v[6:9], v201 offset:22112
	v_exp_f32_e32 v78, v78
	v_exp_f32_e32 v79, v79
	v_add_f32_e32 v200, v200, v72
	v_add_f32_e32 v200, v200, v73
	v_add_f32_e32 v200, v200, v74
	v_add_f32_e32 v200, v200, v75
	v_add_f32_e32 v200, v200, v76
	s_waitcnt lgkmcnt(2)
	v_mfma_f32_32x32x16_bf16 v[80:95], v[202:205], v[10:13], v[80:95]
	ds_read_b128 v[10:13], v201 offset:26720
	v_cvt_pk_bf16_f32 v206, v72, v73
	v_cvt_pk_bf16_f32 v207, v74, v75
	v_cvt_pk_bf16_f32 v208, v76, v77
	v_cvt_pk_bf16_f32 v209, v78, v79
	v_add_f32_e32 v200, v200, v77
	v_add_f32_e32 v200, v200, v78
	v_add_f32_e32 v200, v200, v79
	s_waitcnt lgkmcnt(2)
	v_mfma_f32_32x32x16_bf16 v[48:63], v[206:209], v[2:5], v[48:63]
	ds_read_b128 v[2:5], v201 offset:31328
	s_waitcnt lgkmcnt(2)
	v_mfma_f32_32x32x16_bf16 v[32:47], v[206:209], v[6:9], v[32:47]
	s_waitcnt lgkmcnt(1)
	v_mfma_f32_32x32x16_bf16 v[16:31], v[206:209], v[10:13], v[16:31]
	s_waitcnt lgkmcnt(0)
	v_mfma_f32_32x32x16_bf16 v[80:95], v[206:209], v[2:5], v[80:95]
	v_cndmask_b32_e64 v201, v14, 1.0, s[6:7]
	v_fmac_f32_e32 v200, v199, v201
	v_mov_b32_e32 v199, v200
	s_branch .LBB0_1465

; __device__ __forceinline__ int crow(int r, int hi) { return (r & 3) + 8 * (r >> 2) + 4 * hi; }
; template <bool WITH_O>
; __device__ __forceinline__ void softmax_step(float& m, float& l, f32x16 (&o)[4], f32x16& p0, f32x16& p1, LAS float* wsf, int r32, int hi) {
;     float mxa = fmaxf(fmaxf(p0[0], p1[0]), p0[1]), mxb = fmaxf(fmaxf(p1[1], p0[2]), p1[2]);
; #pragma unroll
;     for (int r = 3; r < 15; r += 2) { mxa = fmaxf(fmaxf(mxa, p0[r]), p1[r]); mxb = fmaxf(fmaxf(mxb, p0[r + 1]), p1[r + 1]); }
;     float mx = fmaxf(fmaxf(mxa, mxb), fmaxf(p0[15], p1[15]));
;     mx = fmaxf(mx, __shfl_xor(mx, 32));
;     const bool grow = __any(mx > m + 8.f);
;     const float mnew = grow ? fmaxf(m, mx) : m;
;     const float f = grow ? __builtin_amdgcn_exp2f(m - mnew) : 1.f;
;     m = mnew;
;     float s = 0.f;
; #pragma unroll
;     for (int r = 0; r < 16; ++r) { p0[r] = __builtin_amdgcn_exp2f(p0[r] - mnew); p1[r] = __builtin_amdgcn_exp2f(p1[r] - mnew); s += p0[r] + p1[r]; }
;     l = l * f + s;
;     if (WITH_O) {
;         if (grow) {
;             if (hi == 0) wsf[r32] = f;
;             asm volatile("s_waitcnt lgkmcnt(0)" ::: "memory");
; #pragma unroll
;             for (int r = 0; r < 16; ++r) { const float fr = wsf[crow(r, hi)];
; #pragma unroll
;                 for (int db = 0; db < 4; ++db) o[db][r] *= fr; }
.Lsel_join:
	v_max3_f32 v0, v2, v5, v3
	v_max3_f32 v79, v7, v4, v8
	v_max3_f32 v0, v0, v9, v14
	v_max3_f32 v79, v79, v6, v11
	v_max3_f32 v0, v0, v12, v66
	v_max3_f32 v79, v79, v10, v15
	v_max3_f32 v0, v0, v64, v70
	v_max3_f32 v79, v79, v13, v67
	v_max3_f32 v0, v0, v68, v96
	v_max3_f32 v79, v79, v65, v71
	v_max3_f32 v0, v0, v72, v97
	v_max3_f32 v79, v79, v69, v74
	v_max_f32_e32 v99, v78, v78
	v_max_f32_e32 v100, v77, v77
	v_max3_f32 v0, v0, v75, v98
	v_max3_f32 v79, v79, v73, v76
	v_max_f32_e32 v99, v100, v99
	v_max3_f32 v0, v0, v79, v99
	v_mov_b32_e32 v79, v0
	s_nop 1
	v_permlane32_swap_b32_e32 v79, v0
	v_max_f32_e32 v0, v0, v79
	v_add_f32_e32 v79, 0x41000000, v200
	v_cmp_gt_f32_e32 vcc, v0, v79
	s_cmp_eq_u64 vcc, 0
	v_max_f32_e32 v79, v200, v200
	v_max_f32_e32 v0, v79, v0
	s_cselect_b64 s[6:7], -1, 0
	v_cndmask_b32_e64 v0, v0, v200, s[6:7]
	v_sub_f32_e32 v79, v200, v0
	v_exp_f32_e32 v79, v79
	s_and_b64 vcc, exec, s[6:7]
	s_cbranch_vccnz .LBB0_1463
	s_and_saveexec_b64 s[8:9], s[4:5]
	ds_write_b32 v192, v79
	s_or_b64 exec, exec, s[8:9]
	s_waitcnt lgkmcnt(0)
	ds_read_b128 v[100:103], v193 offset:96
	ds_read_b128 v[104:107], v193 offset:64
	ds_read_b128 v[108:111], v193 offset:32
	ds_read_b128 v[200:203], v193
	s_waitcnt lgkmcnt(3)
	v_pk_mul_f32 v[60:61], v[60:61], v[100:101]
	s_waitcnt lgkmcnt(2)
	v_pk_mul_f32 v[56:57], v[56:57], v[104:105]
	s_waitcnt lgkmcnt(1)
	v_pk_mul_f32 v[52:53], v[52:53], v[108:109]
	v_pk_mul_f32 v[62:63], v[62:63], v[102:103]
	v_pk_mul_f32 v[58:59], v[58:59], v[106:107]
	v_pk_mul_f32 v[54:55], v[54:55], v[110:111]
	s_waitcnt lgkmcnt(0)
	v_pk_mul_f32 v[50:51], v[50:51], v[202:203]
	v_pk_mul_f32 v[48:49], v[48:49], v[200:201]
	v_pk_mul_f32 v[44:45], v[44:45], v[100:101]
	v_pk_mul_f32 v[40:41], v[40:41], v[104:105]
	v_pk_mul_f32 v[36:37], v[36:37], v[108:109]
	v_pk_mul_f32 v[46:47], v[46:47], v[102:103]
	v_pk_mul_f32 v[42:43], v[42:43], v[106:107]
	v_pk_mul_f32 v[38:39], v[38:39], v[110:111]
	v_pk_mul_f32 v[34:35], v[34:35], v[202:203]
	v_pk_mul_f32 v[32:33], v[32:33], v[200:201]
	v_pk_mul_f32 v[28:29], v[28:29], v[100:101]
	v_pk_mul_f32 v[24:25], v[24:25], v[104:105]
	v_pk_mul_f32 v[20:21], v[20:21], v[108:109]
	v_pk_mul_f32 v[30:31], v[30:31], v[102:103]
	v_pk_mul_f32 v[26:27], v[26:27], v[106:107]
	v_pk_mul_f32 v[22:23], v[22:23], v[110:111]
	v_pk_mul_f32 v[18:19], v[18:19], v[202:203]
	v_pk_mul_f32 v[16:17], v[16:17], v[200:201]
	v_pk_mul_f32 v[92:93], v[92:93], v[100:101]
	v_pk_mul_f32 v[88:89], v[88:89], v[104:105]
	v_pk_mul_f32 v[84:85], v[84:85], v[108:109]
	v_pk_mul_f32 v[94:95], v[94:95], v[102:103]
	v_pk_mul_f32 v[90:91], v[90:91], v[106:107]
	v_pk_mul_f32 v[86:87], v[86:87], v[110:111]
	v_pk_mul_f32 v[82:83], v[82:83], v[202:203]
	v_pk_mul_f32 v[80:81], v[80:81], v[200:201]

; __device__ __forceinline__ int crow(int r, int hi) { return (r & 3) + 8 * (r >> 2) + 4 * hi; }
; template <bool WITH_O>
; __device__ __forceinline__ void softmax_step(float& m, float& l, f32x16 (&o)[4], f32x16& p0, f32x16& p1, LAS float* wsf, int r32, int hi) {
;     float mxa = fmaxf(fmaxf(p0[0], p1[0]), p0[1]), mxb = fmaxf(fmaxf(p1[1], p0[2]), p1[2]);
; #pragma unroll
;     for (int r = 3; r < 15; r += 2) { mxa = fmaxf(fmaxf(mxa, p0[r]), p1[r]); mxb = fmaxf(fmaxf(mxb, p0[r + 1]), p1[r + 1]); }
;     float mx = fmaxf(fmaxf(mxa, mxb), fmaxf(p0[15], p1[15]));
;     mx = fmaxf(mx, __shfl_xor(mx, 32));
;     const bool grow = __any(mx > m + 8.f);
;     const float mnew = grow ? fmaxf(m, mx) : m;
;     const float f = grow ? __builtin_amdgcn_exp2f(m - mnew) : 1.f;
;     m = mnew;
;     float s = 0.f;
; #pragma unroll
;     for (int r = 0; r < 16; ++r) { p0[r] = __builtin_amdgcn_exp2f(p0[r] - mnew); p1[r] = __builtin_amdgcn_exp2f(p1[r] - mnew); s += p0[r] + p1[r]; }
;     l = l * f + s;
;     if (WITH_O) {
;         if (grow) {
;             if (hi == 0) wsf[r32] = f;
;             asm volatile("s_waitcnt lgkmcnt(0)" ::: "memory");
; #pragma unroll
;             for (int r = 0; r < 16; ++r) { const float fr = wsf[crow(r, hi)];
; #pragma unroll
;                 for (int db = 0; db < 4; ++db) o[db][r] *= fr; }
; __device__ __forceinline__ void nsa_unit(int hk, int T, LAS unsigned char* lds, LAS float* wsf, const AttnPtrs& P) {
;     ...
;                 for (int r = 0; r < 16; ++r) { const int key = 64 * j + crow(r, hi);
;                     if (key > tq || key <= tq - 512) p0[r] = -INFINITY; if (key + 32 > tq || key + 32 <= tq - 512) p1[r] = -INFINITY; }
;             }
;             softmax_step<true>(m, l, o, p0, p1, wsf, r32, hi);
.LBB0_1480:
	s_nop 4
	v_max3_f32 v0, v80, v96, v81
	v_max3_f32 v2, v97, v82, v98
	v_max3_f32 v0, v0, v83, v99
	v_max3_f32 v2, v2, v84, v100
	v_max3_f32 v0, v0, v85, v101
	v_max3_f32 v2, v2, v86, v102
	v_max3_f32 v0, v0, v87, v103
	v_max3_f32 v2, v2, v88, v104
	v_max3_f32 v0, v0, v89, v105
	v_max3_f32 v2, v2, v90, v106
	v_max3_f32 v0, v0, v91, v107
	v_max3_f32 v2, v2, v92, v108
	v_max_f32_e32 v3, v111, v111
	v_max_f32_e32 v4, v95, v95
	v_max3_f32 v0, v0, v93, v109
	v_max3_f32 v2, v2, v94, v110
	v_max_f32_e32 v3, v4, v3
	v_max3_f32 v0, v0, v2, v3
	v_mov_b32_e32 v2, v0
	s_nop 1
	v_permlane32_swap_b32_e32 v2, v0
	v_max_f32_e32 v0, v0, v2
	v_add_f32_e32 v2, 0x41000000, v190
	v_cmp_gt_f32_e32 vcc, v0, v2
	s_cmp_eq_u64 vcc, 0
	v_max_f32_e32 v2, v190, v190
	v_max_f32_e32 v0, v2, v0
	s_cselect_b64 s[6:7], -1, 0
	v_cndmask_b32_e64 v0, v0, v190, s[6:7]
	v_sub_f32_e32 v2, v190, v0
	v_exp_f32_e32 v3, v2
	s_and_b64 vcc, exec, s[6:7]
	s_cbranch_vccnz .LBB0_1484
	s_and_saveexec_b64 s[10:11], s[4:5]
	ds_write_b32 v192, v3
	s_or_b64 exec, exec, s[10:11]
	s_waitcnt lgkmcnt(0)
	ds_read_b128 v[4:7], v193 offset:96
	ds_read_b128 v[8:11], v193 offset:64
	ds_read_b128 v[12:15], v193 offset:32
	ds_read_b128 v[194:197], v193
	s_waitcnt lgkmcnt(3)
	v_pk_mul_f32 v[76:77], v[76:77], v[4:5]
	s_waitcnt lgkmcnt(2)
	v_pk_mul_f32 v[72:73], v[72:73], v[8:9]
	s_waitcnt lgkmcnt(1)
	v_pk_mul_f32 v[68:69], v[68:69], v[12:13]
	v_pk_mul_f32 v[78:79], v[78:79], v[6:7]
	v_pk_mul_f32 v[74:75], v[74:75], v[10:11]
	v_pk_mul_f32 v[70:71], v[70:71], v[14:15]
	s_waitcnt lgkmcnt(0)
	v_pk_mul_f32 v[66:67], v[66:67], v[196:197]
	v_pk_mul_f32 v[64:65], v[64:65], v[194:195]
	v_pk_mul_f32 v[60:61], v[60:61], v[4:5]
	v_pk_mul_f32 v[56:57], v[56:57], v[8:9]
	v_pk_mul_f32 v[52:53], v[52:53], v[12:13]
	v_pk_mul_f32 v[62:63], v[62:63], v[6:7]
	v_pk_mul_f32 v[58:59], v[58:59], v[10:11]
	v_pk_mul_f32 v[54:55], v[54:55], v[14:15]
	v_pk_mul_f32 v[50:51], v[50:51], v[196:197]
	v_pk_mul_f32 v[48:49], v[48:49], v[194:195]
	v_pk_mul_f32 v[44:45], v[44:45], v[4:5]
	v_pk_mul_f32 v[40:41], v[40:41], v[8:9]
	v_pk_mul_f32 v[36:37], v[36:37], v[12:13]
	v_pk_mul_f32 v[46:47], v[46:47], v[6:7]
	v_pk_mul_f32 v[42:43], v[42:43], v[10:11]
	v_pk_mul_f32 v[38:39], v[38:39], v[14:15]
	v_pk_mul_f32 v[34:35], v[34:35], v[196:197]
	v_pk_mul_f32 v[32:33], v[32:33], v[194:195]
	v_pk_mul_f32 v[28:29], v[28:29], v[4:5]
	v_pk_mul_f32 v[24:25], v[24:25], v[8:9]
	v_pk_mul_f32 v[20:21], v[20:21], v[12:13]
	v_pk_mul_f32 v[30:31], v[30:31], v[6:7]
	v_pk_mul_f32 v[26:27], v[26:27], v[10:11]
	v_pk_mul_f32 v[22:23], v[22:23], v[14:15]
	v_pk_mul_f32 v[18:19], v[18:19], v[196:197]
	v_pk_mul_f32 v[16:17], v[16:17], v[194:195]

; __device__ __forceinline__ int crow(int r, int hi) { return (r & 3) + 8 * (r >> 2) + 4 * hi; }
; template <bool WITH_O>
; __device__ __forceinline__ void softmax_step(float& m, float& l, f32x16 (&o)[4], f32x16& p0, f32x16& p1, LAS float* wsf, int r32, int hi) {
;     float mxa = fmaxf(fmaxf(p0[0], p1[0]), p0[1]), mxb = fmaxf(fmaxf(p1[1], p0[2]), p1[2]);
; #pragma unroll
;     for (int r = 3; r < 15; r += 2) { mxa = fmaxf(fmaxf(mxa, p0[r]), p1[r]); mxb = fmaxf(fmaxf(mxb, p0[r + 1]), p1[r + 1]); }
;     float mx = fmaxf(fmaxf(mxa, mxb), fmaxf(p0[15], p1[15]));
;     mx = fmaxf(mx, __shfl_xor(mx, 32));
;     const bool grow = __any(mx > m + 8.f);
;     const float mnew = grow ? fmaxf(m, mx) : m;
;     const float f = grow ? __builtin_amdgcn_exp2f(m - mnew) : 1.f;
;     m = mnew;
;     float s = 0.f;
; #pragma unroll
;     for (int r = 0; r < 16; ++r) { p0[r] = __builtin_amdgcn_exp2f(p0[r] - mnew); p1[r] = __builtin_amdgcn_exp2f(p1[r] - mnew); s += p0[r] + p1[r]; }
;     l = l * f + s;
;     if (WITH_O) {
;         if (grow) {
;             if (hi == 0) wsf[r32] = f;
;             asm volatile("s_waitcnt lgkmcnt(0)" ::: "memory");
; #pragma unroll
;             for (int r = 0; r < 16; ++r) { const float fr = wsf[crow(r, hi)];
; #pragma unroll
;                 for (int db = 0; db < 4; ++db) o[db][r] *= fr; }
; __device__ __forceinline__ void mla_unit(int h, int qb, LAS unsigned char* lds, LAS float* wsf, const AttnPtrs& P) {
;     ...
;                 for (int r = 0; r < 16; ++r) { const int key = 64 * t + crow(r, hi); if (key > qrow) p0[r] = -INFINITY; if (key + 32 > qrow) p1[r] = -INFINITY; }
;             }
;             softmax_step<true>(m, l, o, p0, p1, wsf, r32, hi);
.LBB0_1497:
	s_nop 8
	v_max3_f32 v189, v68, v84, v69
	v_max3_f32 v191, v85, v70, v86
	v_max3_f32 v189, v189, v71, v87
	v_max3_f32 v191, v191, v72, v88
	v_max3_f32 v189, v189, v73, v89
	v_max3_f32 v191, v191, v74, v90
	v_max3_f32 v189, v189, v75, v91
	v_max3_f32 v191, v191, v76, v92
	v_max3_f32 v189, v189, v77, v93
	v_max3_f32 v191, v191, v78, v94
	v_max3_f32 v189, v189, v79, v95
	v_max3_f32 v191, v191, v80, v96
	v_max_f32_e32 v192, v99, v99
	v_max_f32_e32 v193, v83, v83
	v_max3_f32 v189, v189, v81, v97
	v_max3_f32 v191, v191, v82, v98
	v_max_f32_e32 v192, v193, v192
	v_max3_f32 v189, v189, v191, v192
	v_mov_b32_e32 v191, v189
	s_nop 1
	v_permlane32_swap_b32_e32 v191, v189
	v_max_f32_e32 v189, v189, v191
	v_add_f32_e32 v191, 0x41000000, v190
	v_cmp_gt_f32_e32 vcc, v189, v191
	s_cmp_eq_u64 vcc, 0
	v_max_f32_e32 v191, v190, v190
	v_max_f32_e32 v189, v191, v189
	s_cselect_b64 s[6:7], -1, 0
	v_cndmask_b32_e64 v189, v189, v190, s[6:7]
	v_sub_f32_e32 v190, v190, v189
	v_exp_f32_e32 v190, v190
	s_and_b64 vcc, exec, s[6:7]
	s_cbranch_vccnz .LBB0_1501
	s_and_saveexec_b64 s[12:13], s[4:5]
	ds_write_b32 v180, v190
	s_or_b64 exec, exec, s[12:13]
	s_waitcnt lgkmcnt(0)
	v_add_u32_e32 v191, s49, v0
	ds_read_b128 v[192:195], v191 offset:96
	ds_read_b128 v[196:199], v191 offset:64
	ds_read_b128 v[200:203], v191 offset:32
	ds_read_b128 v[204:207], v191
	s_waitcnt lgkmcnt(3)
	v_pk_mul_f32 v[14:15], v[14:15], v[192:193]
	s_waitcnt lgkmcnt(2)
	v_pk_mul_f32 v[10:11], v[10:11], v[196:197]
	s_waitcnt lgkmcnt(1)
	v_pk_mul_f32 v[6:7], v[6:7], v[200:201]
	v_pk_mul_f32 v[16:17], v[16:17], v[194:195]
	v_pk_mul_f32 v[12:13], v[12:13], v[198:199]
	v_pk_mul_f32 v[8:9], v[8:9], v[202:203]
	s_waitcnt lgkmcnt(0)
	v_pk_mul_f32 v[4:5], v[4:5], v[206:207]
	v_pk_mul_f32 v[2:3], v[2:3], v[204:205]
	v_pk_mul_f32 v[62:63], v[62:63], v[192:193]
	v_pk_mul_f32 v[58:59], v[58:59], v[196:197]
	v_pk_mul_f32 v[54:55], v[54:55], v[200:201]
	v_pk_mul_f32 v[64:65], v[64:65], v[194:195]
	v_pk_mul_f32 v[60:61], v[60:61], v[198:199]
	v_pk_mul_f32 v[56:57], v[56:57], v[202:203]
	v_pk_mul_f32 v[52:53], v[52:53], v[206:207]
	v_pk_mul_f32 v[50:51], v[50:51], v[204:205]
	v_pk_mul_f32 v[46:47], v[46:47], v[192:193]
	v_pk_mul_f32 v[42:43], v[42:43], v[196:197]
	v_pk_mul_f32 v[38:39], v[38:39], v[200:201]
	v_pk_mul_f32 v[48:49], v[48:49], v[194:195]
	v_pk_mul_f32 v[44:45], v[44:45], v[198:199]
	v_pk_mul_f32 v[40:41], v[40:41], v[202:203]
	v_pk_mul_f32 v[36:37], v[36:37], v[206:207]
	v_pk_mul_f32 v[34:35], v[34:35], v[204:205]
	v_pk_mul_f32 v[30:31], v[30:31], v[192:193]
	v_pk_mul_f32 v[26:27], v[26:27], v[196:197]
	v_pk_mul_f32 v[22:23], v[22:23], v[200:201]
	v_pk_mul_f32 v[32:33], v[32:33], v[194:195]
	v_pk_mul_f32 v[28:29], v[28:29], v[198:199]
	v_pk_mul_f32 v[24:25], v[24:25], v[202:203]
	v_pk_mul_f32 v[20:21], v[20:21], v[206:207]
	v_pk_mul_f32 v[18:19], v[18:19], v[204:205]
